# grid barrier: every non-leader WG also issues an L2 write-back on arrival so the XCD leader's final write-back finds less dirty data
# baseline (speedup 1.0000x reference)
.Lgs0_b173:
	s_or_b64 exec, exec, s[18:19]
	v_cvt_f32_u32_e32 v4, v2
	s_waitcnt vmcnt(0)
	v_readfirstlane_b32 s18, v3
	v_sub_u32_e32 v3, 0, v2
	v_rcp_iflag_f32_e32 v4, v4
	v_add_u32_e32 v5, s18, v1
	v_mul_f32_e32 v4, 0x4f7ffffe, v4
	v_cvt_u32_f32_e32 v4, v4
	v_mul_lo_u32 v1, v3, v4
	v_mul_hi_u32 v1, v4, v1
	v_add_u32_e32 v1, v4, v1
	v_mul_hi_u32 v1, v5, v1
	v_mul_lo_u32 v3, v1, v2
	v_sub_u32_e32 v3, v5, v3
	v_add_u32_e32 v4, 1, v1
	v_cmp_ge_u32_e32 vcc, v3, v2
	s_nop 1
	v_cndmask_b32_e32 v1, v1, v4, vcc
	v_sub_u32_e32 v4, v3, v2
	v_cndmask_b32_e32 v3, v3, v4, vcc
	v_add_u32_e32 v4, 1, v1
	v_cmp_ge_u32_e32 vcc, v3, v2
	v_add_u32_e32 v3, 1, v5
	s_nop 0
	v_cndmask_b32_e32 v1, v1, v4, vcc
	v_mul_lo_u32 v4, v2, v1
	v_add_u32_e32 v2, v4, v2
	v_cmp_ne_u32_e32 vcc, v3, v2
	s_and_saveexec_b64 s[18:19], vcc
	s_xor_b64 s[18:19], exec, s[18:19]
	s_cbranch_execz .Lgs0_b187
	buffer_wbl2 sc1
	v_readlane_b32 s22, v255, 0
	v_readlane_b32 s23, v255, 1
	s_waitcnt lgkmcnt(0)
	s_nop 3
	global_load_dword v0, v17, s[22:23] sc1
	s_waitcnt vmcnt(0)
	v_cmp_eq_u32_e32 vcc, v0, v1
	s_and_saveexec_b64 s[22:23], vcc
	s_cbranch_execz .Lgs0_b186
	s_mov_b32 s24, 1
	s_mov_b64 s[28:29], 0
	s_branch .Lgs0_b177

.LBB0_604:
	s_or_b64 exec, exec, s[18:19]
	v_cvt_f32_u32_e32 v4, v2
	s_waitcnt vmcnt(0)
	v_readfirstlane_b32 s18, v3
	v_sub_u32_e32 v3, 0, v2
	v_rcp_iflag_f32_e32 v4, v4
	v_add_u32_e32 v5, s18, v1
	v_mul_f32_e32 v4, 0x4f7ffffe, v4
	v_cvt_u32_f32_e32 v4, v4
	v_mul_lo_u32 v1, v3, v4
	v_mul_hi_u32 v1, v4, v1
	v_add_u32_e32 v1, v4, v1
	v_mul_hi_u32 v1, v5, v1
	v_mul_lo_u32 v3, v1, v2
	v_sub_u32_e32 v3, v5, v3
	v_add_u32_e32 v4, 1, v1
	v_cmp_ge_u32_e32 vcc, v3, v2
	s_nop 1
	v_cndmask_b32_e32 v1, v1, v4, vcc
	v_sub_u32_e32 v4, v3, v2
	v_cndmask_b32_e32 v3, v3, v4, vcc
	v_add_u32_e32 v4, 1, v1
	v_cmp_ge_u32_e32 vcc, v3, v2
	v_add_u32_e32 v3, 1, v5
	s_nop 0
	v_cndmask_b32_e32 v1, v1, v4, vcc
	v_mul_lo_u32 v4, v2, v1
	v_add_u32_e32 v2, v4, v2
	v_cmp_ne_u32_e32 vcc, v3, v2
	s_and_saveexec_b64 s[18:19], vcc
	s_xor_b64 s[18:19], exec, s[18:19]
	s_cbranch_execz .LBB0_618
	buffer_wbl2 sc1
	v_readlane_b32 s22, v255, 0
	v_readlane_b32 s23, v255, 1
	s_waitcnt lgkmcnt(0)
	s_nop 3
	global_load_dword v0, v17, s[22:23] sc1
	s_waitcnt vmcnt(0)
	v_cmp_eq_u32_e32 vcc, v0, v1
	s_and_saveexec_b64 s[22:23], vcc
	s_cbranch_execz .LBB0_617
	s_mov_b32 s24, 1
	s_mov_b64 s[26:27], 0
	s_branch .LBB0_608

.LBB0_674:
	s_or_b64 exec, exec, s[14:15]
	v_cvt_f32_u32_e32 v4, v2
	s_waitcnt vmcnt(0)
	v_readfirstlane_b32 s14, v3
	v_sub_u32_e32 v3, 0, v2
	v_rcp_iflag_f32_e32 v4, v4
	v_add_u32_e32 v5, s14, v1
	v_mul_f32_e32 v4, 0x4f7ffffe, v4
	v_cvt_u32_f32_e32 v4, v4
	v_mul_lo_u32 v1, v3, v4
	v_mul_hi_u32 v1, v4, v1
	v_add_u32_e32 v1, v4, v1
	v_mul_hi_u32 v1, v5, v1
	v_mul_lo_u32 v3, v1, v2
	v_sub_u32_e32 v3, v5, v3
	v_add_u32_e32 v4, 1, v1
	v_cmp_ge_u32_e32 vcc, v3, v2
	s_nop 1
	v_cndmask_b32_e32 v1, v1, v4, vcc
	v_sub_u32_e32 v4, v3, v2
	v_cndmask_b32_e32 v3, v3, v4, vcc
	v_add_u32_e32 v4, 1, v1
	v_cmp_ge_u32_e32 vcc, v3, v2
	v_add_u32_e32 v3, 1, v5
	s_nop 0
	v_cndmask_b32_e32 v1, v1, v4, vcc
	v_mul_lo_u32 v4, v2, v1
	v_add_u32_e32 v2, v4, v2
	v_cmp_ne_u32_e32 vcc, v3, v2
	s_and_saveexec_b64 s[14:15], vcc
	s_xor_b64 s[14:15], exec, s[14:15]
	s_cbranch_execz .LBB0_688
	buffer_wbl2 sc1
	v_readlane_b32 s18, v255, 0
	v_readlane_b32 s19, v255, 1
	s_waitcnt lgkmcnt(0)
	s_nop 3
	global_load_dword v0, v17, s[18:19] sc1
	s_waitcnt vmcnt(0)
	v_cmp_eq_u32_e32 vcc, v0, v1
	s_and_saveexec_b64 s[18:19], vcc
	s_cbranch_execz .LBB0_687
	s_mov_b32 s36, 1
	s_mov_b64 s[22:23], 0
	s_branch .LBB0_678

.LBB0_742:
	s_or_b64 exec, exec, s[14:15]
	v_cvt_f32_u32_e32 v4, v2
	s_waitcnt vmcnt(0)
	v_readfirstlane_b32 s14, v3
	v_sub_u32_e32 v3, 0, v2
	v_rcp_iflag_f32_e32 v4, v4
	v_add_u32_e32 v5, s14, v1
	v_mul_f32_e32 v4, 0x4f7ffffe, v4
	v_cvt_u32_f32_e32 v4, v4
	v_mul_lo_u32 v1, v3, v4
	v_mul_hi_u32 v1, v4, v1
	v_add_u32_e32 v1, v4, v1
	v_mul_hi_u32 v1, v5, v1
	v_mul_lo_u32 v3, v1, v2
	v_sub_u32_e32 v3, v5, v3
	v_add_u32_e32 v4, 1, v1
	v_cmp_ge_u32_e32 vcc, v3, v2
	s_nop 1
	v_cndmask_b32_e32 v1, v1, v4, vcc
	v_sub_u32_e32 v4, v3, v2
	v_cndmask_b32_e32 v3, v3, v4, vcc
	v_add_u32_e32 v4, 1, v1
	v_cmp_ge_u32_e32 vcc, v3, v2
	v_add_u32_e32 v3, 1, v5
	s_nop 0
	v_cndmask_b32_e32 v1, v1, v4, vcc
	v_mul_lo_u32 v4, v2, v1
	v_add_u32_e32 v2, v4, v2
	v_cmp_ne_u32_e32 vcc, v3, v2
	s_and_saveexec_b64 s[14:15], vcc
	s_xor_b64 s[14:15], exec, s[14:15]
	s_cbranch_execz .LBB0_756
	buffer_wbl2 sc1
	v_readlane_b32 s18, v255, 0
	v_readlane_b32 s19, v255, 1
	s_waitcnt lgkmcnt(0)
	s_nop 3
	global_load_dword v0, v17, s[18:19] sc1
	s_waitcnt vmcnt(0)
	v_cmp_eq_u32_e32 vcc, v0, v1
	s_and_saveexec_b64 s[18:19], vcc
	s_cbranch_execz .LBB0_755
	s_mov_b32 s24, 1
	s_mov_b64 s[22:23], 0
	s_branch .LBB0_746
